# scan WGs routed through the generic scan copy with a hand-scheduled loop body (batched LDS reads, operands reloaded in place, no register copies); plus P4/P8/RMSNorm load hoists
# speedup vs baseline: 1.0062x; 1.0062x over previous
; #define LAS __attribute__((address_space(3)))
; __device__ __forceinline__ void gdn_scan_full(const bf16* CHUNK, const float* CD, bf16* OG, LAS unsigned char* lds, int item, int tid, int wave, int lane) {
;     const int d = item >> 5, b = (item >> 4) & 1, h = item & 15;
;     const int ql = lane & 15, gq = lane >> 4, mt = wave & 3, ng = wave >> 2;
;     LAS bf16* Sb = (LAS bf16*)lds;
;     LAS bf16* Vn = Sb + 128 * 136;
;     for (int e = tid; e < 128 * 136 / 2; e += NTHR) ((LAS unsigned*)Sb)[e] = 0u;
;     f32x4 S[8];
; #pragma unroll
;     for (int t = 0; t < 8; ++t) S[t] = (f32x4){0.f, 0.f, 0.f, 0.f};
;     const int jb0 = ((d * 2 + b) * 16 + h) * 64;
;     bf16* og = OG + (size_t)d * M * 2048 + (size_t)b * SEQ * 2048 + h * 128 + 64 * ng + ql;
;     bf16x8_t wf[4], qf[4], inf[2], kf[2]; unsigned short uu[16]; float cdv;
;     bf16x8_t wfn[4], qfn[4], infn[2], kfn[2]; unsigned short uun[16]; float cdn;
.Lscan_generic:
	v_and_b32_e32 v0, 15, v140
	s_bfe_u32 s0, s79, 0x20006
	v_lshlrev_b32_e32 v3, 6, v0
	v_lshrrev_b32_e32 v1, 4, v165
	s_lshl_b32 s13, s0, 11
	s_waitcnt vmcnt(0)
	v_lshl_or_b32 v6, s0, 10, v3
	s_lshl_b32 s14, s0, 4
	s_lshl_b32 s0, s0, 5
	v_lshlrev_b32_e32 v4, 3, v1
	s_add_i32 s0, s0, 0
	s_lshl_b32 s1, s78, 4
	v_add_u32_e32 v195, s0, v4
	s_lshl_b32 s0, s78, 5
	s_and_b32 s12, s1, 0x3fffffc0
	s_add_i32 s0, s0, 0
	v_or_b32_e32 v10, 48, v165
	v_or_b32_e32 v5, s12, v0
	v_add_u32_e32 v8, s0, v4
	s_movk_i32 s0, 0x110
	v_or_b32_e32 v11, s1, v10
	v_mul_lo_u32 v9, v5, s0
	v_mul_lo_u32 v12, v11, s0
	s_movk_i32 s0, 0x90
	v_mul_lo_u32 v197, v5, s0
	v_mul_lo_u32 v198, v11, s0
	s_add_i32 s0, s12, s13
	v_lshl_or_b32 v146, s78, 10, v3
	v_lshlrev_b32_e32 v3, 2, v1
	v_lshl_add_u32 v1, v1, 9, s0
	v_ashrrev_i32_e32 v147, 31, v146
	v_or_b32_e32 v141, s14, v3
	v_and_b32_e32 v7, 48, v140
	v_or_b32_e32 v13, 0x70, v165
	v_or_b32_e32 v144, v1, v0
	v_mov_b32_e32 v145, 0
	v_lshl_or_b32 v2, v0, 7, s13
	v_lshl_add_u32 v148, v141, 7, v5
	v_add_u32_e32 v169, 0, v7
	v_mul_u32_u24_e32 v5, 0x90, v0
	v_mul_u32_u24_e32 v11, 0x90, v10
	v_mul_u32_u24_e32 v14, 0x90, v13
	v_mul_u32_u24_e32 v15, 0x110, v0
	v_mul_u32_u24_e32 v10, 0x110, v10
	v_mul_u32_u24_e32 v13, 0x110, v13
	v_mov_b32_e32 v16, 0xffc
	v_lshlrev_b32_e32 v1, 1, v144
	v_lshlrev_b64 v[166:167], 1, v[146:147]
	v_mov_b32_e32 v149, v145
	v_bitop3_b32 v199, s14, 63, v3 bitop3:0x36
	v_bitop3_b32 v200, s14, 62, v3 bitop3:0x36
	v_bitop3_b32 v201, s14, 61, v3 bitop3:0x36
	v_bitop3_b32 v202, s14, 60, v3 bitop3:0x36
	v_or_b32_e32 v150, 16, v148
	v_mov_b32_e32 v151, v145
	v_or_b32_e32 v152, 32, v148
	v_mov_b32_e32 v153, v145
	v_or_b32_e32 v154, 48, v148
	v_mov_b32_e32 v155, v145
	v_bitop3_b32 v203, s14, v16, v3 bitop3:0x36
	v_or_b32_e32 v156, 0x60, v1
	v_mov_b32_e32 v157, v145
	v_or_b32_e32 v158, 64, v1
	v_mov_b32_e32 v159, v145
	v_or_b32_e32 v160, 32, v1
	v_mov_b32_e32 v161, v145
	v_lshlrev_b64 v[162:163], 1, v[144:145]
	v_lshl_or_b32 v164, v2, 1, v7
	v_or_b32_e32 v166, v166, v7
	v_lshl_or_b32 v168, v6, 1, v7
	v_lshlrev_b32_e32 v170, 1, v2
	v_lshlrev_b32_e32 v172, 1, v4
	s_lshl_b32 s18, s12, 1
	v_lshlrev_b32_e32 v174, 1, v6
	s_mov_b32 s19, 0xc000
	v_lshlrev_b32_e32 v176, 1, v0
	s_mov_b32 s20, 0x5040100
	s_mov_b32 s21, 0x31c16000
	s_mov_b32 s22, 0x31c1a000
	s_mov_b32 s23, 0x31c22000
	s_mov_b32 s34, 0x31c1e000
	s_mov_b32 s35, 0x31c12000
	s_mov_b64 s[12:13], 0x12000
	v_mov_b32_e32 v204, 0x12000
	v_add_u32_e32 v205, v169, v9
	v_add_u32_e32 v206, v169, v12
	v_add_u32_e32 v207, v169, v5
	v_add_u32_e32 v208, v169, v11
	v_add_u32_e32 v209, v169, v14
	v_add_u32_e32 v210, v8, v15
	v_add_u32_e32 v211, v8, v10
	v_add_u32_e32 v212, v8, v13
	s_mov_b32 s36, s88
	s_mov_b32 s37, s88

; #define LAS __attribute__((address_space(3)))
; __device__ __forceinline__ void gdn_scan_full(const bf16* CHUNK, const float* CD, bf16* OG, LAS unsigned char* lds, int item, int tid, int wave, int lane) {
;     ...
;     LAS bf16* Sb = (LAS bf16*)lds;
;     LAS bf16* Vn = Sb + 128 * 136;
;     for (int e = tid; e < 128 * 136 / 2; e += NTHR) ((LAS unsigned*)Sb)[e] = 0u;
;     f32x4 S[8];
; #pragma unroll
;     for (int t = 0; t < 8; ++t) S[t] = (f32x4){0.f, 0.f, 0.f, 0.f};
;     const int jb0 = ((d * 2 + b) * 16 + h) * 64;
;     bf16* og = OG + (size_t)d * M * 2048 + (size_t)b * SEQ * 2048 + h * 128 + 64 * ng + ql;
;     bf16x8_t wf[4], qf[4], inf[2], kf[2]; unsigned short uu[16]; float cdv;
;     bf16x8_t wfn[4], qfn[4], infn[2], kfn[2]; unsigned short uun[16]; float cdn;
;     ...
;     GF_LOAD(0, wfn, qfn, infn, kfn, uun, cdn);
;     __syncthreads();
.LBB0_365:
	v_add_u32_e32 v1, 0x200, v1
	s_movk_i32 s14, 0x1fff
	v_cmp_lt_u32_e32 vcc, s14, v1
	ds_write_b32 v0, v145
	s_or_b64 s[0:1], vcc, s[0:1]
	v_add_u32_e32 v0, 0x800, v0
	s_andn2_b64 exec, exec, s[0:1]
	s_cbranch_execnz .LBB0_365
	s_or_b64 exec, exec, s[0:1]
	s_bfe_u32 s42, s37, 0x10004
	s_and_b32 s0, s37, 0xffffffe0
	s_lshl_b32 s16, s42, 4
	s_or_b32 s0, s0, s16
	s_and_b32 s1, s36, 15
	s_or_b32 s17, s0, s1
	s_lshl_b32 s0, s17, 6
	s_ashr_i32 s1, s0, 31
	s_lshl_b64 s[14:15], s[0:1], 2
	s_add_u32 s38, s14, 0x43c00004
	s_addc_u32 s39, s15, 0
	s_mul_hi_i32 s40, s0, 0x12000
	v_mad_i64_i32 v[178:179], s[14:15], s0, v204, v[156:157]
	v_mad_i64_i32 v[180:181], s[14:15], s0, v204, v[158:159]
	v_mad_i64_i32 v[182:183], s[14:15], s0, v204, v[160:161]
	v_mad_i64_i32 v[184:185], s[14:15], s0, v204, v[162:163]
	v_mad_i64_i32 v[188:189], s[0:1], s0, v204, v[166:167]
	s_and_b32 s0, s37, 0x3ffffe0
	s_and_b32 s43, s37, 15
	s_or_b32 s0, s16, s0
	s_ashr_i32 s14, s37, 5
	s_or_b32 s16, s0, s43
	s_lshl_b32 s0, s16, 6
	s_ashr_i32 s15, s14, 31
	s_mul_i32 s17, s17, 0x480000
	s_lshl_b64 s[14:15], s[14:15], 25
	s_ashr_i32 s1, s0, 31
	s_mul_i32 s16, s16, 0x480000
	v_or_b32_e32 v186, s17, v164
	v_or_b32_e32 v190, s17, v168
	s_mul_hi_i32 s17, s0, 0x12000
	s_add_u32 s16, s33, s16
	s_addc_u32 s17, s82, s17
	v_mov_b32_e32 v171, v145
	v_mov_b32_e32 v173, v145
	v_lshl_add_u64 v[0:1], s[16:17], 0, v[170:171]
	v_mov_b32_e32 v187, s40
	v_mov_b32_e32 v191, s40
	v_lshl_add_u64 v[0:1], v[0:1], 0, v[172:173]
	s_mov_b64 s[40:41], 0x4000
	v_lshl_add_u64 v[2:3], v[0:1], 0, s[40:41]
	s_mov_b64 s[40:41], 0x8000
	v_lshl_add_u64 v[4:5], v[0:1], 0, s[40:41]
	s_movk_i32 s40, 0x4000
	v_add_co_u32_e32 v6, vcc, s40, v0
	v_readlane_b32 s44, v253, 32
	s_nop 0
	v_addc_co_u32_e32 v7, vcc, 0, v1, vcc
	s_mov_b32 s41, 0x8000
	v_readlane_b32 s45, v253, 33
	s_add_u32 s14, s44, s14
	v_add_co_u32_e32 v0, vcc, s41, v0
	s_addc_u32 s15, s45, s15
	s_lshl_b32 s41, s42, 24
	v_addc_co_u32_e32 v1, vcc, 0, v1, vcc
	s_add_u32 s14, s14, s41
	v_mov_b32_e32 v175, v145
	global_load_dwordx4 v[24:27], v[6:7], off
	global_load_dwordx4 v[16:19], v[0:1], off
	global_load_dwordx4 v[28:31], v[2:3], off offset:64
	global_load_dwordx4 v[12:15], v[4:5], off offset:64
	global_load_dwordx4 v[36:39], v[2:3], off offset:128
	global_load_dwordx4 v[8:11], v[4:5], off offset:128
	global_load_dwordx4 v[32:35], v[2:3], off offset:192
	global_load_dwordx4 v[20:23], v[4:5], off offset:192
	s_addc_u32 s15, s15, 0
	s_lshl_b32 s41, s43, 8
	v_lshl_add_u64 v[0:1], s[16:17], 0, v[174:175]
	s_add_u32 s14, s14, s41
	v_lshl_add_u64 v[0:1], v[0:1], 0, v[172:173]
	s_mov_b64 s[42:43], 0x10000
	s_mov_b32 s41, 0x10000
	v_lshl_add_u64 v[2:3], v[0:1], 0, s[42:43]
	v_lshl_add_u64 v[4:5], v[146:147], 1, s[16:17]
	v_add_co_u32_e32 v0, vcc, s41, v0
	s_addc_u32 s15, s15, 0
	v_lshl_add_u64 v[4:5], v[4:5], 0, v[172:173]
	v_addc_co_u32_e32 v1, vcc, 0, v1, vcc
	s_add_u32 s14, s14, s18
	s_mov_b64 s[42:43], 0xc000
	global_load_dwordx4 v[40:43], v[0:1], off
	v_add_co_u32_e32 v0, vcc, s19, v4
	s_addc_u32 s15, s15, 0
	v_lshl_add_u64 v[48:49], v[4:5], 0, s[42:43]
	v_addc_co_u32_e32 v1, vcc, 0, v5, vcc
	v_mov_b32_e32 v177, v145
	global_load_dwordx4 v[4:7], v[0:1], off
	global_load_dwordx4 v[44:47], v[2:3], off offset:64
	s_nop 0
	global_load_dwordx4 v[0:3], v[48:49], off offset:64
	v_lshl_add_u64 v[48:49], v[148:149], 1, s[16:17]
	v_lshl_add_u64 v[50:51], v[150:151], 1, s[16:17]
	v_lshl_add_u64 v[192:193], s[14:15], 0, v[176:177]
	s_lshl_b64 s[0:1], s[0:1], 2
	v_readlane_b32 s14, v253, 40
	global_load_ushort v175, v[48:49], off
	global_load_ushort v52, v[48:49], off offset:256
	global_load_ushort v53, v[48:49], off offset:512
	global_load_ushort v173, v[48:49], off offset:768
	global_load_ushort v171, v[48:49], off offset:32
	global_load_ushort v54, v[50:51], off offset:256
	global_load_ushort v55, v[50:51], off offset:512
	global_load_ushort v214, v[50:51], off offset:768
	global_load_ushort v213, v[48:49], off offset:64
	v_lshl_add_u64 v[50:51], v[152:153], 1, s[16:17]
	s_add_u32 s0, s14, s0
	v_readlane_b32 s14, v253, 41
	global_load_ushort v56, v[50:51], off offset:256
	global_load_ushort v57, v[50:51], off offset:512
	global_load_ushort v216, v[50:51], off offset:768
	global_load_ushort v215, v[48:49], off offset:96
	v_lshl_add_u64 v[48:49], v[154:155], 1, s[16:17]
	s_addc_u32 s1, s14, s1
	global_load_ushort v50, v[48:49], off offset:256
	global_load_ushort v51, v[48:49], off offset:512
	global_load_ushort v217, v[48:49], off offset:768
	global_load_dword v194, v145, s[0:1]
	s_cmp_lt_u32 s37, 32
	v_mov_b32_e32 v48, 0
	s_mov_b32 s40, 0
	s_cselect_b64 vcc, -1, 0
	v_mov_b32_e32 v177, v203
	v_mov_b32_e32 v49, v48
	v_mov_b32_e32 v58, v48
	v_mov_b32_e32 v59, v48
	v_mov_b32_e32 v60, v48
	v_mov_b32_e32 v61, v48
	v_mov_b32_e32 v62, v48
	v_mov_b32_e32 v63, v48
	v_mov_b32_e32 v64, v48
	v_mov_b32_e32 v65, v48
	v_mov_b32_e32 v66, v48
	v_mov_b32_e32 v67, v48
	v_mov_b32_e32 v68, v48
	v_mov_b32_e32 v69, v48
	v_mov_b32_e32 v70, v48
	v_mov_b32_e32 v71, v48
	v_mov_b32_e32 v76, v48
	v_mov_b32_e32 v77, v48
	v_mov_b32_e32 v78, v48
	v_mov_b32_e32 v79, v48
	v_mov_b32_e32 v72, v48
	v_mov_b32_e32 v73, v48
	v_mov_b32_e32 v74, v48
	v_mov_b32_e32 v75, v48
	s_waitcnt lgkmcnt(0)
	s_barrier
	s_waitcnt vmcnt(14)
	v_perm_b32 v228, v53, v52, s20
	s_waitcnt vmcnt(10)
	v_perm_b32 v227, v55, v54, s20
	v_mov_b32_e32 v52, v48
	v_mov_b32_e32 v53, v48
	v_mov_b32_e32 v54, v48
	s_waitcnt vmcnt(6)
	v_perm_b32 v226, v57, v56, s20
	v_mov_b32_e32 v55, v48
	v_mov_b32_e32 v56, v48
	v_mov_b32_e32 v57, v48
	s_waitcnt vmcnt(2)
	v_perm_b32 v144, v51, v50, s20
	v_mov_b32_e32 v50, v48
	v_mov_b32_e32 v51, v48
	s_waitcnt vmcnt(0)
; #define LAS __attribute__((address_space(3)))
; #define LDS_BARRIER() do { asm volatile("s_waitcnt lgkmcnt(0)" ::: "memory"); __builtin_amdgcn_s_barrier(); asm volatile("" ::: "memory"); } while (0)
; __device__ __forceinline__ unsigned f2bf(float f) { return pk2(f, f) & 0xffffu; }
; __device__ __forceinline__ void gdn_scan_full(const bf16* CHUNK, const float* CD, bf16* OG, LAS unsigned char* lds, int item, int tid, int wave, int lane) {
;     ...
;     for (int n = 0; n < 64; ++n) {
; #pragma unroll
;         for (int s = 0; s < 4; ++s) { wf[s] = wfn[s]; qf[s] = qfn[s]; }
; #pragma unroll
;         for (int s = 0; s < 2; ++s) { inf[s] = infn[s]; kf[s] = kfn[s]; }
; #pragma unroll
;         for (int j = 0; j < 16; ++j) uu[j] = uun[j];
;         cdv = cdn;
;         if (n + 1 < 64) GF_LOAD(n + 1, wfn, qfn, infn, kfn, uun, cdn);
;         f32x4 wsum[4], os[4];
; #pragma unroll
;         for (int t = 0; t < 4; ++t) { wsum[t] = (f32x4){0.f, 0.f, 0.f, 0.f}; os[t] = (f32x4){0.f, 0.f, 0.f, 0.f}; }
; #pragma unroll
;         for (int t = 0; t < 4; ++t)
; #pragma unroll
;             for (int s = 0; s < 4; ++s) { const bf16x8_t sf = *(const LAS bf16x8_t*)(Sb + (64 * ng + 16 * t + ql) * 136 + 32 * s + 8 * gq);
;                 wsum[t] = __builtin_amdgcn_mfma_f32_16x16x32_bf16(wf[s], sf, wsum[t], 0, 0, 0); os[t] = __builtin_amdgcn_mfma_f32_16x16x32_bf16(qf[s], sf, os[t], 0, 0, 0); }
; #pragma unroll
;         for (int t = 0; t < 4; ++t) { s16x4_t vn;
; #pragma unroll
;             for (int j = 0; j < 4; ++j) vn[j] = (short)f2bf(__uint_as_float((unsigned)uu[t * 4 + j] << 16) - wsum[t][j]);
;             *(LAS s16x4_t*)(Vn + (64 * ng + 16 * t + ql) * 72 + 16 * mt + 4 * gq) = vn; }
;         LDS_BARRIER();
.LBB0_367:
	v_add_u32_e32 v108, v195, v197
	v_add_u32_e32 v104, v195, v198
	v_add_u32_e32 v105, v169, v197
	v_add_u32_e32 v96, v169, v198
	ds_read_b128 v[80:83], v205
	ds_read_b128 v[84:87], v205 offset:64
	ds_read_b128 v[88:91], v205 offset:128
	ds_read_b128 v[92:95], v205 offset:192
	ds_read_b128 v[100:103], v205 offset:4352
	ds_read_b128 v[112:115], v205 offset:4416
	ds_read_b128 v[116:119], v205 offset:4480
	ds_read_b128 v[120:123], v205 offset:4544
	s_waitcnt lgkmcnt(7)
	v_mfma_f32_16x16x32_bf16 v[124:127], v[24:27], v[80:83], 0
	v_mul_f32_e32 v72, v194, v72
	v_mfma_f32_16x16x32_bf16 v[230:233], v[16:19], v[80:83], 0
	v_mul_f32_e32 v73, v194, v73
	ds_read_b128 v[80:83], v205 offset:8704
	s_waitcnt lgkmcnt(7)
	v_mfma_f32_16x16x32_bf16 v[124:127], v[28:31], v[84:87], v[124:127]
	v_mul_f32_e32 v74, v194, v74
	v_mfma_f32_16x16x32_bf16 v[230:233], v[12:15], v[84:87], v[230:233]
	v_mul_f32_e32 v75, v194, v75
	ds_read_b128 v[84:87], v205 offset:8768
	s_waitcnt lgkmcnt(7)
	v_mfma_f32_16x16x32_bf16 v[124:127], v[36:39], v[88:91], v[124:127]
	v_mul_f32_e32 v76, v194, v76
	v_mfma_f32_16x16x32_bf16 v[230:233], v[8:11], v[88:91], v[230:233]
	v_mul_f32_e32 v77, v194, v77
	ds_read_b128 v[88:91], v205 offset:8832
	s_waitcnt lgkmcnt(7)
	v_mfma_f32_16x16x32_bf16 v[124:127], v[32:35], v[92:95], v[124:127]
	v_mul_f32_e32 v78, v194, v78
	v_mfma_f32_16x16x32_bf16 v[230:233], v[20:23], v[92:95], v[230:233]
	v_mul_f32_e32 v79, v194, v79
	ds_read_b128 v[92:95], v205 offset:8896
	s_waitcnt lgkmcnt(7)
	v_mfma_f32_16x16x32_bf16 v[128:131], v[24:27], v[100:103], 0
	v_mul_f32_e32 v68, v194, v68
	v_mfma_f32_16x16x32_bf16 v[234:237], v[16:19], v[100:103], 0
	v_mul_f32_e32 v69, v194, v69
	ds_read_b128 v[100:103], v206
	v_lshlrev_b32_e32 v196, 16, v175
	v_lshlrev_b32_e32 v229, 16, v228
	s_waitcnt lgkmcnt(7)
	v_mfma_f32_16x16x32_bf16 v[128:131], v[28:31], v[112:115], v[128:131]
	v_mul_f32_e32 v70, v194, v70
	v_mfma_f32_16x16x32_bf16 v[234:237], v[12:15], v[112:115], v[234:237]
	v_mul_f32_e32 v71, v194, v71
	ds_read_b128 v[112:115], v206 offset:64
	v_and_b32_e32 v250, 0xffff0000, v228
	v_lshlrev_b32_e32 v251, 16, v173
	s_waitcnt lgkmcnt(7)
	v_mfma_f32_16x16x32_bf16 v[128:131], v[36:39], v[116:119], v[128:131]
	v_mul_f32_e32 v64, v194, v64
	v_mfma_f32_16x16x32_bf16 v[234:237], v[8:11], v[116:119], v[234:237]
	v_mul_f32_e32 v65, v194, v65
	ds_read_b128 v[116:119], v206 offset:128
	v_sub_f32_e32 v196, v196, v124
	v_sub_f32_e32 v229, v229, v125
	s_waitcnt lgkmcnt(7)
	v_mfma_f32_16x16x32_bf16 v[128:131], v[32:35], v[120:123], v[128:131]
	v_mul_f32_e32 v66, v194, v66
	v_mfma_f32_16x16x32_bf16 v[234:237], v[20:23], v[120:123], v[234:237]
	v_mul_f32_e32 v67, v194, v67
	ds_read_b128 v[120:123], v206 offset:192
	v_sub_f32_e32 v250, v250, v126
	v_sub_f32_e32 v251, v251, v127
	s_waitcnt lgkmcnt(7)
	v_mfma_f32_16x16x32_bf16 v[132:135], v[24:27], v[80:83], 0
	v_mul_f32_e32 v60, v194, v60
	v_mfma_f32_16x16x32_bf16 v[238:241], v[16:19], v[80:83], 0
	v_mul_f32_e32 v61, v194, v61
	v_cvt_pk_bf16_f32 v98, v196, v229
	v_cvt_pk_bf16_f32 v99, v250, v251
	s_waitcnt lgkmcnt(6)
	v_mfma_f32_16x16x32_bf16 v[132:135], v[28:31], v[84:87], v[132:135]
	v_mul_f32_e32 v62, v194, v62
	v_mfma_f32_16x16x32_bf16 v[238:241], v[12:15], v[84:87], v[238:241]
	v_mul_f32_e32 v63, v194, v63
	ds_write_b64 v108, v[98:99] offset:34816
	v_lshlrev_b32_e32 v196, 16, v171
	s_waitcnt lgkmcnt(6)
	v_mfma_f32_16x16x32_bf16 v[132:135], v[36:39], v[88:91], v[132:135]
	v_mul_f32_e32 v56, v194, v56
	v_mfma_f32_16x16x32_bf16 v[238:241], v[8:11], v[88:91], v[238:241]
	v_mul_f32_e32 v57, v194, v57
	v_lshlrev_b32_e32 v229, 16, v227
	v_and_b32_e32 v250, 0xffff0000, v227
	s_waitcnt lgkmcnt(5)
	v_mfma_f32_16x16x32_bf16 v[132:135], v[32:35], v[92:95], v[132:135]
	v_mul_f32_e32 v58, v194, v58
	v_mfma_f32_16x16x32_bf16 v[238:241], v[20:23], v[92:95], v[238:241]
	v_mul_f32_e32 v59, v194, v59
	v_lshlrev_b32_e32 v251, 16, v214
	v_sub_f32_e32 v196, v196, v128
	s_waitcnt lgkmcnt(4)
	v_mfma_f32_16x16x32_bf16 v[136:139], v[24:27], v[100:103], 0
	v_mul_f32_e32 v52, v194, v52
	v_mfma_f32_16x16x32_bf16 v[242:245], v[16:19], v[100:103], 0
	v_mul_f32_e32 v53, v194, v53
	v_sub_f32_e32 v229, v229, v129
	v_sub_f32_e32 v250, v250, v130
	s_waitcnt lgkmcnt(3)
	v_mfma_f32_16x16x32_bf16 v[136:139], v[28:31], v[112:115], v[136:139]
	v_mul_f32_e32 v54, v194, v54
	v_mfma_f32_16x16x32_bf16 v[242:245], v[12:15], v[112:115], v[242:245]
	v_mul_f32_e32 v55, v194, v55
	v_sub_f32_e32 v251, v251, v131
	v_cvt_pk_bf16_f32 v106, v196, v229
	s_waitcnt lgkmcnt(2)
	v_mfma_f32_16x16x32_bf16 v[136:139], v[36:39], v[116:119], v[136:139]
	v_mul_f32_e32 v48, v194, v48
	v_mfma_f32_16x16x32_bf16 v[242:245], v[8:11], v[116:119], v[242:245]
	v_mul_f32_e32 v49, v194, v49
	v_cvt_pk_bf16_f32 v107, v250, v251
	ds_write_b64 v108, v[106:107] offset:37120
	s_waitcnt lgkmcnt(2)
; #define LAS __attribute__((address_space(3)))
; #define LDS_BARRIER() do { asm volatile("s_waitcnt lgkmcnt(0)" ::: "memory"); __builtin_amdgcn_s_barrier(); asm volatile("" ::: "memory"); } while (0)
; __device__ __forceinline__ unsigned f2bf(float f) { return pk2(f, f) & 0xffffu; }
; __device__ __forceinline__ void gdn_scan_full(const bf16* CHUNK, const float* CD, bf16* OG, LAS unsigned char* lds, int item, int tid, int wave, int lane) {
;     ...
;         if (n + 1 < 64) GF_LOAD(n + 1, wfn, qfn, infn, kfn, uun, cdn);
;         f32x4 wsum[4], os[4];
; #pragma unroll
;         for (int t = 0; t < 4; ++t) { wsum[t] = (f32x4){0.f, 0.f, 0.f, 0.f}; os[t] = (f32x4){0.f, 0.f, 0.f, 0.f}; }
; #pragma unroll
;         for (int t = 0; t < 4; ++t)
; #pragma unroll
;             for (int s = 0; s < 4; ++s) { const bf16x8_t sf = *(const LAS bf16x8_t*)(Sb + (64 * ng + 16 * t + ql) * 136 + 32 * s + 8 * gq);
;                 wsum[t] = __builtin_amdgcn_mfma_f32_16x16x32_bf16(wf[s], sf, wsum[t], 0, 0, 0); os[t] = __builtin_amdgcn_mfma_f32_16x16x32_bf16(qf[s], sf, os[t], 0, 0, 0); }
; #pragma unroll
;         for (int t = 0; t < 4; ++t) { s16x4_t vn;
; #pragma unroll
;             for (int j = 0; j < 4; ++j) vn[j] = (short)f2bf(__uint_as_float((unsigned)uu[t * 4 + j] << 16) - wsum[t][j]);
;             *(LAS s16x4_t*)(Vn + (64 * ng + 16 * t + ql) * 72 + 16 * mt + 4 * gq) = vn; }
;         LDS_BARRIER();
; #pragma unroll
;         for (int t = 0; t < 4; ++t)
; #pragma unroll
;             for (int s = 0; s < 2; ++s) { const bf16x8_t vf = *(const LAS bf16x8_t*)(Vn + (64 * ng + 16 * t + ql) * 72 + 32 * s + 8 * gq); os[t] = __builtin_amdgcn_mfma_f32_16x16x32_bf16(inf[s], vf, os[t], 0, 0, 0); }
	v_mfma_f32_16x16x32_bf16 v[136:139], v[32:35], v[120:123], v[136:139]
	v_mul_f32_e32 v50, v194, v50
	v_mfma_f32_16x16x32_bf16 v[242:245], v[20:23], v[120:123], v[242:245]
	v_mul_f32_e32 v51, v194, v51
	v_lshlrev_b32_e32 v196, 16, v213
	v_lshlrev_b32_e32 v229, 16, v226
	s_add_u32 s0, s28, s21
	s_addc_u32 s1, s29, 0
	v_lshl_add_u64 v[246:247], s[0:1], 0, v[186:187]
	s_add_u32 s0, s28, s22
	s_addc_u32 s1, s29, 0
	v_lshl_add_u64 v[248:249], s[0:1], 0, v[186:187]
	v_and_b32_e32 v250, 0xffff0000, v226
	v_lshlrev_b32_e32 v251, 16, v216
	v_sub_f32_e32 v196, v196, v132
	v_sub_f32_e32 v229, v229, v133
	global_load_dwordx4 v[24:27], v[246:247], off
	global_load_dwordx4 v[16:19], v[248:249], off
	v_sub_f32_e32 v250, v250, v134
	v_sub_f32_e32 v251, v251, v135
	v_cvt_pk_bf16_f32 v110, v196, v229
	global_load_dwordx4 v[28:31], v[246:247], off offset:64
	global_load_dwordx4 v[12:15], v[248:249], off offset:64
	v_cvt_pk_bf16_f32 v111, v250, v251
	ds_write_b64 v108, v[110:111] offset:39424
	v_lshlrev_b32_e32 v196, 16, v215
	global_load_dwordx4 v[36:39], v[246:247], off offset:128
	global_load_dwordx4 v[8:11], v[248:249], off offset:128
	v_lshlrev_b32_e32 v229, 16, v144
	v_and_b32_e32 v250, 0xffff0000, v144
	v_lshlrev_b32_e32 v251, 16, v217
	global_load_dwordx4 v[32:35], v[246:247], off offset:192
	global_load_dwordx4 v[20:23], v[248:249], off offset:192
	v_sub_f32_e32 v196, v196, v136
	v_sub_f32_e32 v229, v229, v137
	v_sub_f32_e32 v250, v250, v138
	v_sub_f32_e32 v251, v251, v139
	v_cvt_pk_bf16_f32 v98, v196, v229
	v_cvt_pk_bf16_f32 v99, v250, v251
	ds_write_b64 v104, v[98:99] offset:34816
	s_add_u32 s0, s28, s35
	s_addc_u32 s1, s29, 0
	v_lshl_add_u64 v[246:247], s[0:1], 0, v[184:185]
	v_lshl_add_u64 v[248:249], s[0:1], 0, v[182:183]
	global_load_ushort v175, v[246:247], off
	global_load_ushort v219, v[246:247], off offset:256
	global_load_ushort v218, v[246:247], off offset:512
	global_load_ushort v173, v[246:247], off offset:768
	global_load_ushort v171, v[246:247], off offset:32
	global_load_ushort v221, v[248:249], off offset:256
	global_load_ushort v220, v[248:249], off offset:512
	global_load_ushort v214, v[248:249], off offset:768
	global_load_ushort v213, v[246:247], off offset:64
	global_load_ushort v215, v[246:247], off offset:96
	v_lshl_add_u64 v[98:99], s[0:1], 0, v[180:181]
	v_lshl_add_u64 v[106:107], s[0:1], 0, v[178:179]
	global_load_ushort v223, v[98:99], off offset:256
	global_load_ushort v222, v[98:99], off offset:512
	global_load_ushort v216, v[98:99], off offset:768
	global_load_ushort v225, v[106:107], off offset:256
	global_load_ushort v224, v[106:107], off offset:512
	global_load_ushort v217, v[106:107], off offset:768
	s_add_u32 s0, s28, s38
	s_addc_u32 s1, s29, s39
	s_nop 0
	global_load_dword v194, v145, s[0:1]
	s_add_u32 s38, s38, 4
	s_addc_u32 s39, s39, 0
	s_waitcnt lgkmcnt(0)
	s_barrier
	ds_read_b128 v[80:83], v105 offset:34816
	ds_read_b128 v[84:87], v105 offset:34880
	ds_read_b128 v[88:91], v105 offset:37120
	ds_read_b128 v[92:95], v105 offset:37184
	ds_read_b128 v[100:103], v105 offset:39424
	ds_read_b128 v[112:115], v105 offset:39488
	ds_read_b128 v[116:119], v96 offset:34816
	ds_read_b128 v[120:123], v96 offset:34880
	ds_read_b128 v[124:127], v207 offset:34816
	ds_read_b128 v[128:131], v207 offset:34880
	ds_read_b128 v[132:135], v207 offset:37120
	ds_read_b128 v[136:139], v207 offset:37184
	ds_read_b128 v[246:249], v207 offset:39424
	s_waitcnt vmcnt(43)
	s_waitcnt lgkmcnt(12)
	v_mfma_f32_16x16x32_bf16 v[230:233], v[40:43], v[80:83], v[230:233]
	ds_read_b128 v[80:83], v207 offset:39488
	s_waitcnt lgkmcnt(12)
	v_mfma_f32_16x16x32_bf16 v[230:233], v[44:47], v[84:87], v[230:233]
	ds_read_b128 v[84:87], v208 offset:34816
	s_waitcnt lgkmcnt(12)
	v_mfma_f32_16x16x32_bf16 v[234:237], v[40:43], v[88:91], v[234:237]
	ds_read_b128 v[88:91], v208 offset:34880
	s_waitcnt lgkmcnt(12)
	v_mfma_f32_16x16x32_bf16 v[234:237], v[44:47], v[92:95], v[234:237]
	ds_read_b128 v[92:95], v207 offset:44032
	s_waitcnt lgkmcnt(12)
	v_mfma_f32_16x16x32_bf16 v[238:241], v[40:43], v[100:103], v[238:241]
	ds_read_b128 v[100:103], v207 offset:44096
	s_waitcnt lgkmcnt(12)
	v_mfma_f32_16x16x32_bf16 v[238:241], v[44:47], v[112:115], v[238:241]
	ds_read_b128 v[112:115], v207 offset:46336
	s_waitcnt lgkmcnt(12)
	v_mfma_f32_16x16x32_bf16 v[242:245], v[40:43], v[116:119], v[242:245]
	ds_read_b128 v[116:119], v207 offset:46400
	s_waitcnt lgkmcnt(12)
; #define LAS __attribute__((address_space(3)))
; #define LDS_BARRIER() do { asm volatile("s_waitcnt lgkmcnt(0)" ::: "memory"); __builtin_amdgcn_s_barrier(); asm volatile("" ::: "memory"); } while (0)
; __device__ __forceinline__ unsigned f2bf(float f) { return pk2(f, f) & 0xffffu; }
; __device__ __forceinline__ void gdn_scan_full(const bf16* CHUNK, const float* CD, bf16* OG, LAS unsigned char* lds, int item, int tid, int wave, int lane) {
;     ...
;         for (int t = 0; t < 4; ++t)
; #pragma unroll
;             for (int s = 0; s < 2; ++s) { const bf16x8_t vf = *(const LAS bf16x8_t*)(Vn + (64 * ng + 16 * t + ql) * 72 + 32 * s + 8 * gq); os[t] = __builtin_amdgcn_mfma_f32_16x16x32_bf16(inf[s], vf, os[t], 0, 0, 0); }
; #pragma unroll
;         for (int j = 0; j < 4; ++j) { const int c = n * 64 + 16 * mt + 4 * gq + j; const int tok = d ? SEQ - 1 - c : c;
; #pragma unroll
;             for (int t = 0; t < 4; ++t) og[(size_t)tok * 2048 + 16 * t] = (bf16)f2bf(os[t][j]); }
; #pragma unroll
;         for (int t = 0; t < 8; ++t) S[t] = S[t] * cdv;
; #pragma unroll
;         for (int t = 0; t < 8; ++t)
; #pragma unroll
;             for (int s = 0; s < 2; ++s) { const bf16x8_t v0 = *(const LAS bf16x8_t*)(Vn + (16 * t + ql) * 72 + 32 * s + 8 * gq); S[t] = __builtin_amdgcn_mfma_f32_16x16x32_bf16(kf[s], v0, S[t], 0, 0, 0); }
; #pragma unroll
;         for (int t = 0; t < 8; ++t) { s16x4_t p;
; #pragma unroll
;             for (int j = 0; j < 4; ++j) p[j] = (short)f2bf(S[t][j]);
;             *(LAS s16x4_t*)(Sb + (16 * t + ql) * 136 + 16 * wave + 4 * gq) = p; }
;         LDS_BARRIER();
	v_mfma_f32_16x16x32_bf16 v[242:245], v[44:47], v[120:123], v[242:245]
	ds_read_b128 v[120:123], v207 offset:48640
	s_add_u32 s0, s28, s23
	s_addc_u32 s1, s29, 0
	v_lshl_add_u64 v[110:111], s[0:1], 0, v[190:191]
	global_load_dwordx4 v[40:43], v[110:111], off
	global_load_dwordx4 v[44:47], v[110:111], off offset:64
	v_add_u32_e32 v252, s40, v141
	v_add_u32_e32 v97, 3, v177
	v_cndmask_b32_e32 v97, v97, v252, vcc
	v_lshlrev_b32_e32 v144, 12, v97
	v_lshl_add_u64 v[98:99], v[192:193], 0, v[144:145]
	v_cvt_pk_bf16_f32 v109, v230, v230
	global_store_short v[98:99], v109, off
	v_cvt_pk_bf16_f32 v109, v234, v234
	global_store_short v[98:99], v109, off offset:32
	v_cvt_pk_bf16_f32 v109, v238, v238
	global_store_short v[98:99], v109, off offset:64
	v_cvt_pk_bf16_f32 v109, v242, v242
	global_store_short v[98:99], v109, off offset:96
	v_add_u32_e32 v109, 1, v252
	v_add_u32_e32 v97, 2, v177
	v_cndmask_b32_e32 v97, v97, v109, vcc
	v_lshlrev_b32_e32 v144, 12, v97
	v_lshl_add_u64 v[98:99], v[192:193], 0, v[144:145]
	v_cvt_pk_bf16_f32 v109, v231, v231
	global_store_short v[98:99], v109, off
	v_cvt_pk_bf16_f32 v109, v235, v235
	global_store_short v[98:99], v109, off offset:32
	v_cvt_pk_bf16_f32 v109, v239, v239
	global_store_short v[98:99], v109, off offset:64
	v_cvt_pk_bf16_f32 v109, v243, v243
	global_store_short v[98:99], v109, off offset:96
	v_add_u32_e32 v109, 2, v252
	v_add_u32_e32 v97, 1, v177
	v_cndmask_b32_e32 v97, v97, v109, vcc
	v_lshlrev_b32_e32 v144, 12, v97
	v_lshl_add_u64 v[98:99], v[192:193], 0, v[144:145]
	v_cvt_pk_bf16_f32 v109, v232, v232
	global_store_short v[98:99], v109, off
	v_cvt_pk_bf16_f32 v109, v236, v236
	global_store_short v[98:99], v109, off offset:32
	v_cvt_pk_bf16_f32 v109, v240, v240
	global_store_short v[98:99], v109, off offset:64
	v_cvt_pk_bf16_f32 v109, v244, v244
	global_store_short v[98:99], v109, off offset:96
	v_add_u32_e32 v109, 3, v252
	v_cndmask_b32_e32 v97, v177, v109, vcc
	v_lshlrev_b32_e32 v144, 12, v97
	v_lshl_add_u64 v[98:99], v[192:193], 0, v[144:145]
	v_cvt_pk_bf16_f32 v109, v233, v233
	global_store_short v[98:99], v109, off
	v_cvt_pk_bf16_f32 v109, v237, v237
	global_store_short v[98:99], v109, off offset:32
	v_cvt_pk_bf16_f32 v109, v241, v241
	global_store_short v[98:99], v109, off offset:64
	v_cvt_pk_bf16_f32 v109, v245, v245
	global_store_short v[98:99], v109, off offset:96
	ds_read_b128 v[230:233], v207 offset:48704
	ds_read_b128 v[234:237], v209 offset:34816
	ds_read_b128 v[238:241], v209 offset:34880
	s_add_i32 s40, s40, 64
	v_subrev_u32_e32 v177, 64, v177
	s_waitcnt vmcnt(43)
	s_waitcnt lgkmcnt(15)
	v_mfma_f32_16x16x32_bf16 v[72:75], v[4:7], v[124:127], v[72:75]
	s_waitcnt lgkmcnt(14)
	v_mfma_f32_16x16x32_bf16 v[72:75], v[0:3], v[128:131], v[72:75]
	s_waitcnt lgkmcnt(13)
	v_mfma_f32_16x16x32_bf16 v[76:79], v[4:7], v[132:135], v[76:79]
	s_waitcnt lgkmcnt(12)
	v_mfma_f32_16x16x32_bf16 v[76:79], v[0:3], v[136:139], v[76:79]
	s_waitcnt lgkmcnt(11)
	v_mfma_f32_16x16x32_bf16 v[68:71], v[4:7], v[246:249], v[68:71]
	s_waitcnt lgkmcnt(10)
	v_mfma_f32_16x16x32_bf16 v[68:71], v[0:3], v[80:83], v[68:71]
	s_waitcnt lgkmcnt(9)
	v_mfma_f32_16x16x32_bf16 v[64:67], v[4:7], v[84:87], v[64:67]
	s_waitcnt lgkmcnt(8)
	v_mfma_f32_16x16x32_bf16 v[64:67], v[0:3], v[88:91], v[64:67]
	s_waitcnt lgkmcnt(7)
	v_mfma_f32_16x16x32_bf16 v[60:63], v[4:7], v[92:95], v[60:63]
	s_waitcnt lgkmcnt(6)
	v_mfma_f32_16x16x32_bf16 v[60:63], v[0:3], v[100:103], v[60:63]
	s_waitcnt lgkmcnt(5)
	v_mfma_f32_16x16x32_bf16 v[56:59], v[4:7], v[112:115], v[56:59]
	s_waitcnt lgkmcnt(4)
	v_mfma_f32_16x16x32_bf16 v[56:59], v[0:3], v[116:119], v[56:59]
	s_waitcnt lgkmcnt(3)
	v_mfma_f32_16x16x32_bf16 v[52:55], v[4:7], v[120:123], v[52:55]
	s_waitcnt lgkmcnt(2)
	v_mfma_f32_16x16x32_bf16 v[52:55], v[0:3], v[230:233], v[52:55]
	s_waitcnt lgkmcnt(1)
	v_mfma_f32_16x16x32_bf16 v[48:51], v[4:7], v[234:237], v[48:51]
	s_waitcnt lgkmcnt(0)
	v_mfma_f32_16x16x32_bf16 v[48:51], v[0:3], v[238:241], v[48:51]
	s_add_u32 s0, s28, s34
	s_addc_u32 s1, s29, 0
	v_lshl_add_u64 v[110:111], s[0:1], 0, v[188:189]
	global_load_dwordx4 v[4:7], v[110:111], off
	global_load_dwordx4 v[0:3], v[110:111], off offset:64
	v_lshl_add_u64 v[178:179], v[178:179], 0, s[12:13]
	v_lshl_add_u64 v[180:181], v[180:181], 0, s[12:13]
	v_lshl_add_u64 v[182:183], v[182:183], 0, s[12:13]
	v_lshl_add_u64 v[184:185], v[184:185], 0, s[12:13]
	v_lshl_add_u64 v[186:187], v[186:187], 0, s[12:13]
	v_lshl_add_u64 v[188:189], v[188:189], 0, s[12:13]
	v_lshl_add_u64 v[190:191], v[190:191], 0, s[12:13]
	v_cvt_pk_bf16_f32 v98, v72, v73
	v_cvt_pk_bf16_f32 v99, v74, v75
	ds_write_b64 v210, v[98:99]
	v_cvt_pk_bf16_f32 v106, v76, v77
	v_cvt_pk_bf16_f32 v107, v78, v79
	ds_write_b64 v210, v[106:107] offset:4352
	v_cvt_pk_bf16_f32 v98, v68, v69
	v_cvt_pk_bf16_f32 v99, v70, v71
	ds_write_b64 v210, v[98:99] offset:8704
	v_cvt_pk_bf16_f32 v106, v64, v65
	v_cvt_pk_bf16_f32 v107, v66, v67
	ds_write_b64 v211, v[106:107]
	v_cvt_pk_bf16_f32 v98, v60, v61
	v_cvt_pk_bf16_f32 v99, v62, v63
	ds_write_b64 v210, v[98:99] offset:17408
	v_cvt_pk_bf16_f32 v106, v56, v57
	v_cvt_pk_bf16_f32 v107, v58, v59
	ds_write_b64 v210, v[106:107] offset:21760
	v_cvt_pk_bf16_f32 v98, v52, v53
	v_cvt_pk_bf16_f32 v99, v54, v55
	ds_write_b64 v210, v[98:99] offset:26112
	v_cvt_pk_bf16_f32 v106, v48, v49
	v_cvt_pk_bf16_f32 v107, v50, v51
	ds_write_b64 v212, v[106:107]
	s_waitcnt vmcnt(20)
	v_perm_b32 v228, v218, v219, s20
	v_perm_b32 v227, v220, v221, s20
	v_perm_b32 v226, v222, v223, s20
	v_perm_b32 v144, v224, v225, s20
	s_cmpk_lg_i32 s40, 0xfc0
	s_waitcnt lgkmcnt(0)
	s_barrier
	s_cbranch_scc1 .LBB0_367
; #define LAS __attribute__((address_space(3)))
; #define LDS_BARRIER() do { asm volatile("s_waitcnt lgkmcnt(0)" ::: "memory"); __builtin_amdgcn_s_barrier(); asm volatile("" ::: "memory"); } while (0)
; __device__ __forceinline__ unsigned f2bf(float f) { return pk2(f, f) & 0xffffu; }
; __device__ __forceinline__ void gdn_scan_full(const bf16* CHUNK, const float* CD, bf16* OG, LAS unsigned char* lds, int item, int tid, int wave, int lane) {
;     ...
;         if (n + 1 < 64) GF_LOAD(n + 1, wfn, qfn, infn, kfn, uun, cdn);
;         f32x4 wsum[4], os[4];
; #pragma unroll
;         for (int t = 0; t < 4; ++t) { wsum[t] = (f32x4){0.f, 0.f, 0.f, 0.f}; os[t] = (f32x4){0.f, 0.f, 0.f, 0.f}; }
; #pragma unroll
;         for (int t = 0; t < 4; ++t)
; #pragma unroll
;             for (int s = 0; s < 4; ++s) { const bf16x8_t sf = *(const LAS bf16x8_t*)(Sb + (64 * ng + 16 * t + ql) * 136 + 32 * s + 8 * gq);
;                 wsum[t] = __builtin_amdgcn_mfma_f32_16x16x32_bf16(wf[s], sf, wsum[t], 0, 0, 0); os[t] = __builtin_amdgcn_mfma_f32_16x16x32_bf16(qf[s], sf, os[t], 0, 0, 0); }
; #pragma unroll
;         for (int t = 0; t < 4; ++t) { s16x4_t vn;
; #pragma unroll
;             for (int j = 0; j < 4; ++j) vn[j] = (short)f2bf(__uint_as_float((unsigned)uu[t * 4 + j] << 16) - wsum[t][j]);
;             *(LAS s16x4_t*)(Vn + (64 * ng + 16 * t + ql) * 72 + 16 * mt + 4 * gq) = vn; }
;         LDS_BARRIER();
	s_waitcnt vmcnt(0)
	ds_read_b128 v[80:83], v205
	ds_read_b128 v[84:87], v205 offset:64
	v_lshlrev_b32_e32 v103, 16, v219
	v_lshlrev_b32_e32 v102, 16, v175
	s_add_i32 s37, s37, s74
	s_waitcnt lgkmcnt(1)
	v_mfma_f32_16x16x32_bf16 v[88:91], v[24:27], v[80:83], 0
	s_add_i32 s36, s36, s74
	s_cmp_gt_i32 s37, 63
	v_mfma_f32_16x16x32_bf16 v[80:83], v[16:19], v[80:83], 0
	s_waitcnt lgkmcnt(0)
	v_mfma_f32_16x16x32_bf16 v[88:91], v[28:31], v[84:87], v[88:91]
	v_mfma_f32_16x16x32_bf16 v[80:83], v[12:15], v[84:87], v[80:83]
	ds_read_b128 v[84:87], v205 offset:128
	ds_read_b128 v[92:95], v205 offset:192
	s_waitcnt lgkmcnt(1)
	v_mfma_f32_16x16x32_bf16 v[88:91], v[36:39], v[84:87], v[88:91]
	v_mfma_f32_16x16x32_bf16 v[80:83], v[8:11], v[84:87], v[80:83]
	s_waitcnt lgkmcnt(0)
	v_mfma_f32_16x16x32_bf16 v[84:87], v[32:35], v[92:95], v[88:91]
	v_mfma_f32_16x16x32_bf16 v[80:83], v[20:23], v[92:95], v[80:83]
	s_nop 3
	ds_read_b128 v[88:91], v205 offset:4352
	ds_read_b128 v[92:95], v205 offset:4416
	s_nop 0
	v_pk_add_f32 v[84:85], v[102:103], v[84:85] neg_lo:[0,1] neg_hi:[0,1]
	v_lshlrev_b32_e32 v103, 16, v173
	s_waitcnt lgkmcnt(1)
	v_mfma_f32_16x16x32_bf16 v[98:101], v[24:27], v[88:91], 0
	v_lshlrev_b32_e32 v102, 16, v218
	v_pk_add_f32 v[86:87], v[102:103], v[86:87] neg_lo:[0,1] neg_hi:[0,1]
	v_cvt_pk_bf16_f32 v84, v84, v85
	v_mfma_f32_16x16x32_bf16 v[88:91], v[16:19], v[88:91], 0
	v_cvt_pk_bf16_f32 v85, v86, v87
	v_lshlrev_b32_e32 v103, 16, v214
	v_lshlrev_b32_e32 v102, 16, v220
	s_waitcnt lgkmcnt(0)
	v_mfma_f32_16x16x32_bf16 v[98:101], v[28:31], v[92:95], v[98:101]
	v_mfma_f32_16x16x32_bf16 v[88:91], v[12:15], v[92:95], v[88:91]
	ds_read_b128 v[92:95], v205 offset:4480
	ds_read_b128 v[110:113], v205 offset:4544
	s_waitcnt lgkmcnt(1)
	v_mfma_f32_16x16x32_bf16 v[98:101], v[36:39], v[92:95], v[98:101]
	v_mfma_f32_16x16x32_bf16 v[88:91], v[8:11], v[92:95], v[88:91]
	s_waitcnt lgkmcnt(0)
	v_mfma_f32_16x16x32_bf16 v[92:95], v[32:35], v[110:113], v[98:101]
	v_mfma_f32_16x16x32_bf16 v[88:91], v[20:23], v[110:113], v[88:91]
	s_nop 3
	ds_read_b128 v[98:101], v205 offset:8704
	ds_read_b128 v[110:113], v205 offset:8768
	ds_read_b128 v[118:121], v205 offset:8832
	ds_read_b128 v[122:125], v205 offset:8896
	ds_read_b128 v[126:129], v206
	ds_read_b128 v[130:133], v206 offset:64
	ds_read_b128 v[134:137], v206 offset:128
	ds_read_b128 v[178:181], v206 offset:192
	s_waitcnt lgkmcnt(7)
	v_mfma_f32_16x16x32_bf16 v[114:117], v[24:27], v[98:101], 0
	ds_write_b64 v108, v[84:85] offset:34816
	v_pk_add_f32 v[94:95], v[102:103], v[94:95] neg_lo:[0,1] neg_hi:[0,1]
	v_mfma_f32_16x16x32_bf16 v[98:101], v[16:19], v[98:101], 0
	s_waitcnt lgkmcnt(4)
	v_mfma_f32_16x16x32_bf16 v[24:27], v[24:27], v[126:129], 0
	v_mfma_f32_16x16x32_bf16 v[114:117], v[28:31], v[110:113], v[114:117]
	v_mfma_f32_16x16x32_bf16 v[98:101], v[12:15], v[110:113], v[98:101]
	s_waitcnt lgkmcnt(3)
	v_mfma_f32_16x16x32_bf16 v[24:27], v[28:31], v[130:133], v[24:27]
	v_lshlrev_b32_e32 v31, 16, v216
	v_lshlrev_b32_e32 v30, 16, v222
	v_mfma_f32_16x16x32_bf16 v[110:113], v[36:39], v[118:121], v[114:117]
	v_mfma_f32_16x16x32_bf16 v[84:87], v[8:11], v[118:121], v[98:101]
	s_nop 2
	v_lshlrev_b32_e32 v99, 16, v221
	v_lshlrev_b32_e32 v98, 16, v171
	s_waitcnt lgkmcnt(2)
	v_mfma_f32_16x16x32_bf16 v[24:27], v[36:39], v[134:137], v[24:27]
	v_add_f32_e64 v92, v98, -v92
	v_add_f32_e64 v93, v99, -v93
	v_or_b32_e32 v36, 0xfc0, v141
	v_cvt_pk_bf16_f32 v92, v92, v93
	v_mfma_f32_16x16x32_bf16 v[98:101], v[32:35], v[122:125], v[110:113]
	v_cvt_pk_bf16_f32 v93, v94, v95
	ds_write_b64 v108, v[92:93] offset:37120
	v_lshlrev_b32_e32 v93, 16, v223
	v_lshlrev_b32_e32 v92, 16, v213
	s_waitcnt lgkmcnt(2)
	v_mfma_f32_16x16x32_bf16 v[24:27], v[32:35], v[178:181], v[24:27]
	s_nop 1
	v_add_f32_e64 v92, v92, -v98
	v_add_f32_e64 v93, v93, -v99
	v_pk_add_f32 v[30:31], v[30:31], v[100:101] neg_lo:[0,1] neg_hi:[0,1]
	v_cvt_pk_bf16_f32 v28, v92, v93
	v_mfma_f32_16x16x32_bf16 v[16:19], v[16:19], v[126:129], 0
	v_cvt_pk_bf16_f32 v29, v30, v31
	ds_write_b64 v108, v[28:29] offset:39424
	v_lshlrev_b32_e32 v29, 16, v225
	v_lshlrev_b32_e32 v28, 16, v215
	v_pk_add_f32 v[24:25], v[28:29], v[24:25] neg_lo:[0,1] neg_hi:[0,1]
	s_waitcnt vmcnt(17)
	v_lshlrev_b32_e32 v29, 16, v217
	v_lshlrev_b32_e32 v28, 16, v224
	v_mfma_f32_16x16x32_bf16 v[12:15], v[12:15], v[130:133], v[16:19]
	v_cvt_pk_bf16_f32 v24, v24, v25
	v_cndmask_b32_e32 v36, v199, v36, vcc
	v_lshlrev_b32_e32 v144, 12, v36
	v_pk_add_f32 v[16:17], v[28:29], v[26:27] neg_lo:[0,1] neg_hi:[0,1]
	v_mfma_f32_16x16x32_bf16 v[8:11], v[8:11], v[134:137], v[12:15]
	v_cvt_pk_bf16_f32 v25, v16, v17
	ds_write_b64 v104, v[24:25] offset:34816
	s_waitcnt lgkmcnt(0)
	s_barrier
; #define LAS __attribute__((address_space(3)))
; #define LDS_BARRIER() do { asm volatile("s_waitcnt lgkmcnt(0)" ::: "memory"); __builtin_amdgcn_s_barrier(); asm volatile("" ::: "memory"); } while (0)
; __device__ __forceinline__ unsigned f2bf(float f) { return pk2(f, f) & 0xffffu; }
; __device__ __forceinline__ void gdn_scan_full(const bf16* CHUNK, const float* CD, bf16* OG, LAS unsigned char* lds, int item, int tid, int wave, int lane) {
;     ...
;         LDS_BARRIER();
; #pragma unroll
;         for (int t = 0; t < 4; ++t)
; #pragma unroll
;             for (int s = 0; s < 2; ++s) { const bf16x8_t vf = *(const LAS bf16x8_t*)(Vn + (64 * ng + 16 * t + ql) * 72 + 32 * s + 8 * gq); os[t] = __builtin_amdgcn_mfma_f32_16x16x32_bf16(inf[s], vf, os[t], 0, 0, 0); }
; #pragma unroll
;         for (int j = 0; j < 4; ++j) { const int c = n * 64 + 16 * mt + 4 * gq + j; const int tok = d ? SEQ - 1 - c : c;
; #pragma unroll
;             for (int t = 0; t < 4; ++t) og[(size_t)tok * 2048 + 16 * t] = (bf16)f2bf(os[t][j]); }
; #pragma unroll
;         for (int t = 0; t < 8; ++t) S[t] = S[t] * cdv;
; #pragma unroll
;         for (int t = 0; t < 8; ++t)
; #pragma unroll
;             for (int s = 0; s < 2; ++s) { const bf16x8_t v0 = *(const LAS bf16x8_t*)(Vn + (16 * t + ql) * 72 + 32 * s + 8 * gq); S[t] = __builtin_amdgcn_mfma_f32_16x16x32_bf16(kf[s], v0, S[t], 0, 0, 0); }
; #pragma unroll
;         for (int t = 0; t < 8; ++t) { s16x4_t p;
; #pragma unroll
;             for (int j = 0; j < 4; ++j) p[j] = (short)f2bf(S[t][j]);
;             *(LAS s16x4_t*)(Sb + (16 * t + ql) * 136 + 16 * wave + 4 * gq) = p; }
;         LDS_BARRIER();
;     }
;     __syncthreads();
	ds_read_b128 v[12:15], v105 offset:34816
	ds_read_b128 v[16:19], v105 offset:34880
	s_waitcnt lgkmcnt(1)
	v_mfma_f32_16x16x32_bf16 v[12:15], v[40:43], v[12:15], v[80:83]
	v_mfma_f32_16x16x32_bf16 v[84:87], v[20:23], v[122:125], v[84:87]
	v_mfma_f32_16x16x32_bf16 v[8:11], v[20:23], v[178:181], v[8:11]
	s_waitcnt lgkmcnt(0)
	v_mfma_f32_16x16x32_bf16 v[12:15], v[44:47], v[16:19], v[12:15]
	ds_read_b128 v[16:19], v105 offset:37120
	ds_read_b128 v[20:23], v105 offset:37184
	ds_read_b128 v[24:27], v105 offset:39424
	ds_read_b128 v[28:31], v105 offset:39488
	s_waitcnt lgkmcnt(3)
	v_mfma_f32_16x16x32_bf16 v[16:19], v[40:43], v[16:19], v[88:91]
	s_nop 1
	v_cvt_pk_bf16_f32 v12, v12, s0
	s_waitcnt lgkmcnt(2)
	v_mfma_f32_16x16x32_bf16 v[16:19], v[44:47], v[20:23], v[16:19]
	ds_read_b128 v[20:23], v96 offset:34816
	ds_read_b128 v[32:35], v96 offset:34880
	ds_read_b128 v[36:39], v207 offset:39488
	s_waitcnt lgkmcnt(2)
	v_mfma_f32_16x16x32_bf16 v[8:11], v[40:43], v[20:23], v[8:11]
	ds_read_b128 v[20:23], v207 offset:34880
	v_mfma_f32_16x16x32_bf16 v[24:27], v[40:43], v[24:27], v[84:87]
	ds_read_b128 v[40:43], v208 offset:34816
	s_waitcnt lgkmcnt(3)
	v_mfma_f32_16x16x32_bf16 v[8:11], v[44:47], v[32:35], v[8:11]
	ds_read_b128 v[32:35], v207 offset:39424
	v_mfma_f32_16x16x32_bf16 v[24:27], v[44:47], v[28:31], v[24:27]
	v_lshl_add_u64 v[28:29], v[192:193], 0, v[144:145]
	s_nop 4
	v_cvt_pk_bf16_f32 v8, v8, s0
	global_store_short v[28:29], v8, off offset:96
	v_or_b32_e32 v8, 0xfc1, v141
	global_store_short v[28:29], v12, off
	v_cvt_pk_bf16_f32 v12, v16, s0
	v_cndmask_b32_e32 v8, v200, v8, vcc
	global_store_short v[28:29], v12, off offset:32
	v_cvt_pk_bf16_f32 v12, v24, s0
	v_lshlrev_b32_e32 v144, 12, v8
	global_store_short v[28:29], v12, off offset:64
	v_cvt_pk_bf16_f32 v16, v13, s0
	v_lshl_add_u64 v[12:13], v[192:193], 0, v[144:145]
	v_cvt_pk_bf16_f32 v8, v17, s0
	global_store_short v[12:13], v8, off offset:32
	v_cvt_pk_bf16_f32 v8, v25, s0
	global_store_short v[12:13], v8, off offset:64
	v_cvt_pk_bf16_f32 v8, v9, s0
	global_store_short v[12:13], v8, off offset:96
	v_or_b32_e32 v8, 0xfc2, v141
	v_cndmask_b32_e32 v8, v201, v8, vcc
	v_lshlrev_b32_e32 v144, 12, v8
	global_store_short v[12:13], v16, off
	v_cvt_pk_bf16_f32 v12, v14, s0
	v_lshl_add_u64 v[8:9], v[192:193], 0, v[144:145]
	global_store_short v[8:9], v12, off
	v_cvt_pk_bf16_f32 v12, v18, s0
	global_store_short v[8:9], v12, off offset:32
	v_cvt_pk_bf16_f32 v12, v26, s0
	v_cvt_pk_bf16_f32 v10, v10, s0
	global_store_short v[8:9], v12, off offset:64
	global_store_short v[8:9], v10, off offset:96
	v_or_b32_e32 v8, 0xfc3, v141
	v_cndmask_b32_e32 v8, v202, v8, vcc
	v_lshlrev_b32_e32 v144, 12, v8
	v_cvt_pk_bf16_f32 v10, v15, s0
	v_lshl_add_u64 v[8:9], v[192:193], 0, v[144:145]
	global_store_short v[8:9], v10, off
	v_cvt_pk_bf16_f32 v10, v19, s0
	global_store_short v[8:9], v10, off offset:32
	v_cvt_pk_bf16_f32 v10, v27, s0
	ds_read_b128 v[12:15], v207 offset:34816
	ds_read_b128 v[24:27], v207 offset:37120
	ds_read_b128 v[28:31], v207 offset:37184
	global_store_short v[8:9], v10, off offset:64
	v_cvt_pk_bf16_f32 v10, v11, s0
	global_store_short v[8:9], v10, off offset:96
	s_waitcnt vmcnt(32)
	v_pk_mul_f32 v[10:11], v[194:195], v[74:75] op_sel_hi:[0,1]
	v_pk_mul_f32 v[8:9], v[194:195], v[72:73] op_sel_hi:[0,1]
	v_pk_mul_f32 v[18:19], v[194:195], v[78:79] op_sel_hi:[0,1]
	v_pk_mul_f32 v[16:17], v[194:195], v[76:77] op_sel_hi:[0,1]
	s_waitcnt lgkmcnt(2)
	v_mfma_f32_16x16x32_bf16 v[8:11], v[4:7], v[12:15], v[8:11]
	v_mul_f32_e64 v14, v194, v70
	v_mul_f32_e64 v15, v194, v71
	v_pk_mul_f32 v[12:13], v[194:195], v[68:69] op_sel_hi:[0,1]
	ds_read_b128 v[44:47], v208 offset:34880
	s_waitcnt lgkmcnt(2)
	v_mfma_f32_16x16x32_bf16 v[16:19], v[4:7], v[24:27], v[16:19]
	v_mul_f32_e64 v26, v194, v62
	v_mul_f32_e64 v27, v194, v63
	v_pk_mul_f32 v[24:25], v[194:195], v[60:61] op_sel_hi:[0,1]
	v_mfma_f32_16x16x32_bf16 v[12:15], v[4:7], v[32:35], v[12:15]
	v_mul_f32_e64 v34, v194, v54
	v_mul_f32_e64 v35, v194, v55
	v_pk_mul_f32 v[32:33], v[194:195], v[52:53] op_sel_hi:[0,1]
	v_mfma_f32_16x16x32_bf16 v[8:11], v[0:3], v[20:23], v[8:11]
	v_mul_f32_e64 v22, v194, v66
	v_mul_f32_e64 v23, v194, v67
	v_pk_mul_f32 v[20:21], v[194:195], v[64:65] op_sel_hi:[0,1]
	s_waitcnt lgkmcnt(1)
	v_mfma_f32_16x16x32_bf16 v[16:19], v[0:3], v[28:31], v[16:19]
	v_mul_f32_e64 v30, v194, v58
	v_mul_f32_e64 v31, v194, v59
	v_pk_mul_f32 v[28:29], v[194:195], v[56:57] op_sel_hi:[0,1]
	v_cvt_pk_bf16_f32 v11, v10, v11
	v_mfma_f32_16x16x32_bf16 v[12:15], v[0:3], v[36:39], v[12:15]
	v_mul_f32_e64 v38, v194, v50
	v_mul_f32_e64 v39, v194, v51
	v_pk_mul_f32 v[36:37], v[194:195], v[48:49] op_sel_hi:[0,1]
	v_cvt_pk_bf16_f32 v19, v18, v19
	v_mfma_f32_16x16x32_bf16 v[20:23], v[4:7], v[40:43], v[20:23]
	ds_read_b128 v[40:43], v207 offset:44032
	ds_read_b128 v[48:51], v207 offset:44096
	ds_read_b128 v[52:55], v207 offset:46336
	ds_read_b128 v[56:59], v207 offset:46400
	v_cvt_pk_bf16_f32 v18, v16, v17
	v_cvt_pk_bf16_f32 v10, v8, v9
	s_waitcnt lgkmcnt(4)
	v_mfma_f32_16x16x32_bf16 v[20:23], v[0:3], v[44:47], v[20:23]
	ds_read_b128 v[44:47], v207 offset:48640
	ds_read_b128 v[60:63], v207 offset:48704
	ds_read_b128 v[64:67], v209 offset:34816
	ds_read_b128 v[68:71], v209 offset:34880
	ds_write_b64 v210, v[18:19] offset:4352
	v_cvt_pk_bf16_f32 v15, v14, v15
	s_waitcnt lgkmcnt(8)
	v_mfma_f32_16x16x32_bf16 v[24:27], v[4:7], v[40:43], v[24:27]
	v_cvt_pk_bf16_f32 v14, v12, v13
	ds_write_b64 v210, v[10:11]
	ds_write_b64 v210, v[14:15] offset:8704
	s_waitcnt lgkmcnt(8)
	v_mfma_f32_16x16x32_bf16 v[16:19], v[4:7], v[52:55], v[28:31]
	v_mfma_f32_16x16x32_bf16 v[8:11], v[0:3], v[48:51], v[24:27]
	s_waitcnt lgkmcnt(7)
	v_mfma_f32_16x16x32_bf16 v[12:15], v[0:3], v[56:59], v[16:19]
	s_nop 4
	v_cvt_pk_bf16_f32 v17, v22, v23
	v_cvt_pk_bf16_f32 v16, v20, v21
	ds_write_b64 v211, v[16:17]
	s_waitcnt lgkmcnt(7)
	v_mfma_f32_16x16x32_bf16 v[16:19], v[4:7], v[44:47], v[32:35]
	v_cvt_pk_bf16_f32 v11, v10, v11
	v_cvt_pk_bf16_f32 v10, v8, v9
	ds_write_b64 v210, v[10:11] offset:17408
	s_waitcnt lgkmcnt(6)
	v_mfma_f32_16x16x32_bf16 v[4:7], v[4:7], v[64:67], v[36:39]
	v_cvt_pk_bf16_f32 v15, v14, v15
	v_cvt_pk_bf16_f32 v14, v12, v13
	ds_write_b64 v210, v[14:15] offset:21760
	v_mfma_f32_16x16x32_bf16 v[8:11], v[0:3], v[60:63], v[16:19]
	s_waitcnt lgkmcnt(6)
	v_mfma_f32_16x16x32_bf16 v[0:3], v[0:3], v[68:71], v[4:7]
	s_nop 5
	v_cvt_pk_bf16_f32 v11, v10, v11
	v_cvt_pk_bf16_f32 v10, v8, v9
	v_cvt_pk_bf16_f32 v3, v2, v3
	v_cvt_pk_bf16_f32 v2, v0, v1
	ds_write_b64 v210, v[10:11] offset:26112
	ds_write_b64 v212, v[2:3]
	s_waitcnt lgkmcnt(0)
	s_barrier
	s_waitcnt lgkmcnt(0)
	s_barrier
	s_cbranch_scc0 .LBB0_364
; __device__ __forceinline__ void attn_issue(const bf16* AQKV, int job, int tid, int wave, int lane, v4u (&kr)[8], v4u (&vr)[8], bf16x8_t (&qf)[4]) {
;     const int bh = job / 96, rem = job - bh * 96, g = rem >> 5, idx = rem & 31;
;     const int b = bh >> 4, h = bh & 15;
;     const int dl = 1 << (2 * g), r = idx & (dl - 1), jp = idx >> (2 * g);
;     const int n = SEQ >> (2 * g);
;     const int kj0 = 128 * jp - 64;
;     const bf16* base = AQKV + (size_t)b * SEQ * 6144 + h * 128;
; #pragma unroll
;     for (int i = 0; i < 8; ++i) { const int id = tid + 512 * i, row = id >> 4, c16 = id & 15, kj = kj0 + row; kr[i] = (v4u){0u, 0u, 0u, 0u};
;         if (kj >= 0 && kj < n) kr[i] = *(const v4u*)(base + (size_t)(kj * dl + r) * 6144 + 2048 + c16 * 8); }
; __global__ void __launch_bounds__(NTHR) fwd(Args args) {
;     ...
;         } else {
;             for (int item = bx; item < 64; item += G) gdn_scan_full(CHUNK, CD, (bf16*)OG, lds, item, tid, wave, lane);
;             if (bx < 3072) attn_issue(AQKV, bx, tid, wave, lane, kr_, vr_, qn_);
;             for (int job = bx; job < 3072; job += G) attn_mfma_job(AQKV, OATT, LSE, lds, job, job + G < 3072 ? job + G : -1, kr_, vr_, qn_, tid, wave, lane);
.LBB0_369:
	s_cmpk_eq_i32 s74, 0x100
	s_cbranch_scc1 .LBB0_526
	s_cmpk_lt_i32 s88, 0xc00
	s_cselect_b64 s[12:13], -1, 0
	s_and_b64 vcc, exec, s[12:13]
	s_cbranch_vccz .LBB0_395
	s_mul_hi_i32 s0, s88, 0x2aaaaaab
	s_lshr_b32 s1, s0, 31
	s_ashr_i32 s0, s0, 4
	s_add_i32 s0, s0, s1
	s_mul_i32 s1, s0, 0xffffffa0
	s_add_i32 s1, s1, s88
	s_ashr_i32 s1, s1, 4
	s_and_b32 s18, s1, -2
	s_and_b32 s14, s88, 31
	s_lshl_b32 s1, -1, s18
	s_andn2_b32 s19, s14, s1
	s_lshr_b32 s1, s14, s18
	s_ashr_i32 s15, s0, 4
	s_lshl_b32 s20, s1, 7
	s_lshr_b32 s16, 0x1000, s18
	s_sub_i32 s17, s20, 64
	s_mul_hi_i32 s14, s15, 0x3000000
	s_mul_i32 s15, s15, 0x3000000
	v_readlane_b32 s22, v253, 36
	v_readlane_b32 s23, v253, 37
	s_add_u32 s15, s22, s15
	s_addc_u32 s21, s23, s14
	s_lshl_b32 s0, s0, 8
	s_and_b32 s0, s0, 0xf00
	s_add_u32 s14, s15, s0
	v_lshlrev_b32_e32 v0, 3, v140
	s_addc_u32 s15, s21, 0
	s_waitcnt vmcnt(0)
	v_and_b32_e32 v4, 0x78, v0
	v_mov_b32_e32 v0, 0
	v_lshrrev_b32_e32 v34, 4, v140
	v_or_b32_e32 v8, s17, v34
	s_cmp_lg_u32 s1, 0
	v_mov_b32_e32 v2, v0
	v_mov_b32_e32 v3, v0
	s_cselect_b64 s[0:1], -1, 0
	v_cmp_gt_i32_e32 vcc, s16, v8
	v_mov_b32_e32 v1, v0
	v_lshlrev_b32_e32 v32, 1, v4
	v_mov_b64_e32 v[6:7], v[2:3]
	s_and_b64 s[22:23], s[0:1], vcc
	v_mov_b64_e32 v[4:5], v[0:1]
	s_and_saveexec_b64 s[0:1], s[22:23]
	s_cbranch_execz .LBB0_372
	v_lshlrev_b32_e32 v4, s18, v8
	v_add_u32_e32 v6, s19, v4
	s_movk_i32 s21, 0x3000
	v_mov_b64_e32 v[4:5], s[14:15]
	v_mad_i64_i32 v[4:5], s[22:23], v6, s21, v[4:5]
	v_mov_b32_e32 v33, v0
	v_lshl_add_u64 v[4:5], v[4:5], 0, v[32:33]
	v_add_co_u32_e32 v4, vcc, 0x1000, v4
	s_nop 1
	v_addc_co_u32_e32 v5, vcc, 0, v5, vcc
	global_load_dwordx4 v[4:7], v[4:5], off

; __global__ void __launch_bounds__(NTHR) fwd(Args args) {
;     ...
;         if (G == 256) {
;             int first, stride, last;
;             if (bx < 64) { gdn_scan_full(CHUNK, CD, (bf16*)OG, lds, bx, tid, wave, lane); first = 0; stride = 1; last = 0; }
.LBB0_430:
	s_branch .Lscan_generic
